# stack: relocated prefetch DMAs + batched prologue row loads + permlane cross-lane sums on top of the deferred row-scale version
# speedup vs baseline: 1.0052x; 1.0049x over previous
.LBB0_727:
	s_add_u32 s42, s46, 0x100
	s_addc_u32 s43, s47, 0
	s_add_i32 s6, 0, 0x10000
	s_cmp_eq_u32 s77, 28
	s_cselect_b32 s51, s29, s43
	s_cselect_b32 s50, s28, s42
	s_cselect_b32 s49, s30, s76
	s_cselect_b32 s48, s74, s75
	s_add_i32 s7, 0, 0x14000
	v_add_u32_e32 v132, s6, v220
	v_add_u32_e32 v160, s7, v220
	ds_read_b128 v[112:115], v132
	ds_read_b128 v[116:119], v132 offset:1024
	ds_read_b128 v[128:131], v132 offset:2048
	ds_read_b128 v[132:135], v132 offset:3072
	ds_read_b128 v[140:143], v160
	ds_read_b128 v[144:147], v160 offset:1024
	ds_read_b128 v[156:159], v160 offset:2048
	ds_read_b128 v[160:163], v160 offset:3072
	v_lshl_add_u64 v[198:199], s[46:47], 0, v[184:185]
	s_add_i32 m0, s52, 0xc000
	ds_read_b128 v[164:167], v222
	ds_read_b128 v[168:171], v222 offset:1024
	ds_read_b128 v[172:175], v222 offset:2048
	ds_read_b128 v[176:179], v222 offset:3072
	ds_read_b128 v[188:191], v222 offset:4096
	ds_read_b128 v[206:209], v222 offset:5120
	ds_read_b128 v[210:213], v222 offset:6144
	ds_read_b128 v[214:217], v222 offset:7168
	global_load_lds_dwordx4 v[198:199], off
	v_lshl_add_u64 v[198:199], s[46:47], 0, v[186:187]
	s_add_i32 m0, s52, 0xe000
	s_nop 0
	global_load_lds_dwordx4 v[198:199], off
	s_waitcnt vmcnt(9)
	s_waitcnt lgkmcnt(0)
	s_barrier
	s_setprio 1
	s_waitcnt lgkmcnt(0)
	v_mfma_f32_16x16x32_bf16 v[152:155], v[112:115], v[164:167], v[152:155]
	v_mfma_f32_16x16x32_bf16 v[148:151], v[128:131], v[164:167], v[148:151]
	v_mfma_f32_16x16x32_bf16 v[108:111], v[112:115], v[172:175], v[108:111]
	v_mfma_f32_16x16x32_bf16 v[104:107], v[128:131], v[172:175], v[104:107]
	v_mfma_f32_16x16x32_bf16 v[92:95], v[112:115], v[188:191], v[92:95]
	v_mfma_f32_16x16x32_bf16 v[88:91], v[128:131], v[188:191], v[88:91]
	v_mfma_f32_16x16x32_bf16 v[76:79], v[112:115], v[210:213], v[76:79]
	v_mfma_f32_16x16x32_bf16 v[72:75], v[128:131], v[210:213], v[72:75]
	v_mfma_f32_16x16x32_bf16 v[152:155], v[116:119], v[168:171], v[152:155]
	v_mfma_f32_16x16x32_bf16 v[148:151], v[132:135], v[168:171], v[148:151]
	v_mfma_f32_16x16x32_bf16 v[108:111], v[116:119], v[176:179], v[108:111]
	v_mfma_f32_16x16x32_bf16 v[104:107], v[132:135], v[176:179], v[104:107]
	v_mfma_f32_16x16x32_bf16 v[92:95], v[116:119], v[206:209], v[92:95]
	v_mfma_f32_16x16x32_bf16 v[88:91], v[132:135], v[206:209], v[88:91]
	v_mfma_f32_16x16x32_bf16 v[76:79], v[116:119], v[214:217], v[76:79]
	v_mfma_f32_16x16x32_bf16 v[72:75], v[132:135], v[214:217], v[72:75]
	s_setprio 0
	s_setprio 1
	v_mfma_f32_16x16x32_bf16 v[124:127], v[140:143], v[164:167], v[124:127]
	v_mfma_f32_16x16x32_bf16 v[120:123], v[156:159], v[164:167], v[120:123]
	v_mfma_f32_16x16x32_bf16 v[100:103], v[140:143], v[172:175], v[100:103]
	v_mfma_f32_16x16x32_bf16 v[96:99], v[156:159], v[172:175], v[96:99]
	v_mfma_f32_16x16x32_bf16 v[84:87], v[140:143], v[188:191], v[84:87]
	v_mfma_f32_16x16x32_bf16 v[80:83], v[156:159], v[188:191], v[80:83]
	v_mfma_f32_16x16x32_bf16 v[68:71], v[140:143], v[210:213], v[68:71]
	v_mfma_f32_16x16x32_bf16 v[64:67], v[156:159], v[210:213], v[64:67]
	v_mfma_f32_16x16x32_bf16 v[124:127], v[144:147], v[168:171], v[124:127]
	v_mfma_f32_16x16x32_bf16 v[120:123], v[160:163], v[168:171], v[120:123]
	v_mfma_f32_16x16x32_bf16 v[100:103], v[144:147], v[176:179], v[100:103]
	v_mfma_f32_16x16x32_bf16 v[96:99], v[160:163], v[176:179], v[96:99]
	v_mfma_f32_16x16x32_bf16 v[84:87], v[144:147], v[206:209], v[84:87]
	v_mfma_f32_16x16x32_bf16 v[80:83], v[160:163], v[206:209], v[80:83]
	v_mfma_f32_16x16x32_bf16 v[68:71], v[144:147], v[214:217], v[68:71]
	v_mfma_f32_16x16x32_bf16 v[64:67], v[160:163], v[214:217], v[64:67]
	s_setprio 0
	s_barrier
	s_add_i32 s6, s6, s25
	v_lshl_add_u64 v[198:199], s[48:49], 0, v[138:139]
	s_mov_b32 m0, s6
	ds_read_b128 v[164:167], v222 offset:16384
	ds_read_b128 v[168:171], v222 offset:17408
	ds_read_b128 v[172:175], v222 offset:18432
	ds_read_b128 v[176:179], v222 offset:19456
	ds_read_b128 v[188:191], v222 offset:20480
	ds_read_b128 v[206:209], v222 offset:21504
	ds_read_b128 v[210:213], v222 offset:22528
	ds_read_b128 v[214:217], v222 offset:23552
	global_load_lds_dwordx4 v[198:199], off
	s_add_i32 m0, s6, 0x2000
	s_add_u32 s46, s48, 0x2000
	v_lshl_add_u64 v[198:199], s[48:49], 0, v[136:137]
	s_addc_u32 s47, s49, 0
	s_add_i32 s6, s7, s25
	global_load_lds_dwordx4 v[198:199], off
	v_lshl_add_u64 v[198:199], s[46:47], 0, v[138:139]
	s_mov_b32 m0, s6
	v_lshl_add_u64 v[200:201], s[50:51], 0, v[180:181]
	global_load_lds_dwordx4 v[198:199], off
	v_lshl_add_u64 v[198:199], s[46:47], 0, v[136:137]
	s_add_i32 m0, s6, 0x2000
	s_nop 0
	global_load_lds_dwordx4 v[198:199], off
	v_lshl_add_u64 v[198:199], s[50:51], 0, v[182:183]
	s_mov_b32 m0, s52
	s_nop 0
	global_load_lds_dwordx4 v[198:199], off
	s_mov_b32 m0, s53
	s_nop 0
	global_load_lds_dwordx4 v[200:201], off
	s_add_i32 vcc_lo, s77, 2
	s_lshl_b32 vcc_lo, vcc_lo, 16
	s_lshl_b32 vcc_hi, s13, 21
	s_add_i32 vcc_lo, vcc_lo, vcc_hi
	s_lshl_b32 vcc_hi, s25, 4
	s_add_i32 vcc_lo, vcc_lo, vcc_hi
	s_lshl_b32 vcc_hi, s12, 10
	s_add_i32 vcc_lo, vcc_lo, vcc_hi
	s_add_u32 vcc_lo, s22, vcc_lo
	s_addc_u32 vcc_hi, s23, 0
	s_mov_b32 m0, 0x22c00
	s_nop 0
	global_load_lds_dwordx4 v224, vcc
	s_waitcnt vmcnt(10)
	s_waitcnt lgkmcnt(0)
	s_barrier
	s_setprio 1
	s_waitcnt lgkmcnt(0)
	v_mfma_f32_16x16x32_bf16 v[60:63], v[112:115], v[164:167], v[60:63]
	v_mfma_f32_16x16x32_bf16 v[56:59], v[128:131], v[164:167], v[56:59]
	v_mfma_f32_16x16x32_bf16 v[44:47], v[112:115], v[172:175], v[44:47]
	v_mfma_f32_16x16x32_bf16 v[40:43], v[128:131], v[172:175], v[40:43]
	v_mfma_f32_16x16x32_bf16 v[28:31], v[112:115], v[188:191], v[28:31]
	v_mfma_f32_16x16x32_bf16 v[24:27], v[128:131], v[188:191], v[24:27]
	v_mfma_f32_16x16x32_bf16 v[12:15], v[112:115], v[210:213], v[12:15]
	v_mfma_f32_16x16x32_bf16 v[8:11], v[128:131], v[210:213], v[8:11]
	v_mfma_f32_16x16x32_bf16 v[60:63], v[116:119], v[168:171], v[60:63]
	v_mfma_f32_16x16x32_bf16 v[56:59], v[132:135], v[168:171], v[56:59]
	v_mfma_f32_16x16x32_bf16 v[44:47], v[116:119], v[176:179], v[44:47]
	v_mfma_f32_16x16x32_bf16 v[40:43], v[132:135], v[176:179], v[40:43]
	v_mfma_f32_16x16x32_bf16 v[28:31], v[116:119], v[206:209], v[28:31]
	v_mfma_f32_16x16x32_bf16 v[24:27], v[132:135], v[206:209], v[24:27]
	v_mfma_f32_16x16x32_bf16 v[12:15], v[116:119], v[214:217], v[12:15]
	v_mfma_f32_16x16x32_bf16 v[8:11], v[132:135], v[214:217], v[8:11]
	s_setprio 0
	s_setprio 1
	v_mfma_f32_16x16x32_bf16 v[52:55], v[140:143], v[164:167], v[52:55]
	v_mfma_f32_16x16x32_bf16 v[48:51], v[156:159], v[164:167], v[48:51]
	v_mfma_f32_16x16x32_bf16 v[36:39], v[140:143], v[172:175], v[36:39]
	v_mfma_f32_16x16x32_bf16 v[32:35], v[156:159], v[172:175], v[32:35]
	v_mfma_f32_16x16x32_bf16 v[20:23], v[140:143], v[188:191], v[20:23]
	v_mfma_f32_16x16x32_bf16 v[16:19], v[156:159], v[188:191], v[16:19]
	v_mfma_f32_16x16x32_bf16 v[4:7], v[140:143], v[210:213], v[4:7]
	v_mfma_f32_16x16x32_bf16 v[0:3], v[156:159], v[210:213], v[0:3]
	v_mfma_f32_16x16x32_bf16 v[52:55], v[144:147], v[168:171], v[52:55]
	v_mfma_f32_16x16x32_bf16 v[48:51], v[160:163], v[168:171], v[48:51]
	v_mfma_f32_16x16x32_bf16 v[36:39], v[144:147], v[176:179], v[36:39]
	v_mfma_f32_16x16x32_bf16 v[32:35], v[160:163], v[176:179], v[32:35]
	v_mfma_f32_16x16x32_bf16 v[20:23], v[144:147], v[206:209], v[20:23]
	v_mfma_f32_16x16x32_bf16 v[16:19], v[160:163], v[206:209], v[16:19]
	v_mfma_f32_16x16x32_bf16 v[4:7], v[144:147], v[214:217], v[4:7]
	v_mfma_f32_16x16x32_bf16 v[0:3], v[160:163], v[214:217], v[0:3]
	s_setprio 0
	s_barrier
	s_add_i32 s6, 0, 0x18000
	s_add_i32 s7, 0, 0x1c000
	v_add_u32_e32 v132, s6, v220
	v_add_u32_e32 v160, s7, v220
	ds_read_b128 v[112:115], v132
	ds_read_b128 v[116:119], v132 offset:1024
	ds_read_b128 v[128:131], v132 offset:2048
	ds_read_b128 v[132:135], v132 offset:3072
	ds_read_b128 v[140:143], v160
	ds_read_b128 v[144:147], v160 offset:1024
	ds_read_b128 v[156:159], v160 offset:2048
	ds_read_b128 v[160:163], v160 offset:3072
	s_add_u32 s46, s50, 0x84000
	s_addc_u32 s47, s51, 0
	s_mov_b32 m0, s54
	v_lshl_add_u64 v[218:219], s[46:47], 0, v[182:183]
	ds_read_b128 v[164:167], v222 offset:32768
	ds_read_b128 v[168:171], v222 offset:33792
	ds_read_b128 v[172:175], v222 offset:34816
	ds_read_b128 v[176:179], v222 offset:35840
	ds_read_b128 v[188:191], v222 offset:36864
	ds_read_b128 v[206:209], v222 offset:37888
	ds_read_b128 v[210:213], v222 offset:38912
	ds_read_b128 v[214:217], v222 offset:39936
	global_load_lds_dwordx4 v[218:219], off
	v_lshl_add_u64 v[218:219], s[46:47], 0, v[180:181]
	s_mov_b32 m0, s55
	s_nop 0
	global_load_lds_dwordx4 v[218:219], off
	s_waitcnt vmcnt(9)
	s_waitcnt lgkmcnt(0)
	s_barrier
	s_setprio 1
	s_waitcnt lgkmcnt(0)
	v_mfma_f32_16x16x32_bf16 v[152:155], v[112:115], v[164:167], v[152:155]
	v_mfma_f32_16x16x32_bf16 v[148:151], v[128:131], v[164:167], v[148:151]
	v_mfma_f32_16x16x32_bf16 v[108:111], v[112:115], v[172:175], v[108:111]
	v_mfma_f32_16x16x32_bf16 v[104:107], v[128:131], v[172:175], v[104:107]
	v_mfma_f32_16x16x32_bf16 v[92:95], v[112:115], v[188:191], v[92:95]
	v_mfma_f32_16x16x32_bf16 v[88:91], v[128:131], v[188:191], v[88:91]
	v_mfma_f32_16x16x32_bf16 v[76:79], v[112:115], v[210:213], v[76:79]
	v_mfma_f32_16x16x32_bf16 v[72:75], v[128:131], v[210:213], v[72:75]
	v_mfma_f32_16x16x32_bf16 v[152:155], v[116:119], v[168:171], v[152:155]
	v_mfma_f32_16x16x32_bf16 v[148:151], v[132:135], v[168:171], v[148:151]
	v_mfma_f32_16x16x32_bf16 v[108:111], v[116:119], v[176:179], v[108:111]
	v_mfma_f32_16x16x32_bf16 v[104:107], v[132:135], v[176:179], v[104:107]
	v_mfma_f32_16x16x32_bf16 v[92:95], v[116:119], v[206:209], v[92:95]
	v_mfma_f32_16x16x32_bf16 v[88:91], v[132:135], v[206:209], v[88:91]
	v_mfma_f32_16x16x32_bf16 v[76:79], v[116:119], v[214:217], v[76:79]
	v_mfma_f32_16x16x32_bf16 v[72:75], v[132:135], v[214:217], v[72:75]
	s_setprio 0
	s_setprio 1
	v_mfma_f32_16x16x32_bf16 v[124:127], v[140:143], v[164:167], v[124:127]
	v_mfma_f32_16x16x32_bf16 v[120:123], v[156:159], v[164:167], v[120:123]
	v_mfma_f32_16x16x32_bf16 v[100:103], v[140:143], v[172:175], v[100:103]
	v_mfma_f32_16x16x32_bf16 v[96:99], v[156:159], v[172:175], v[96:99]
	v_mfma_f32_16x16x32_bf16 v[84:87], v[140:143], v[188:191], v[84:87]
	v_mfma_f32_16x16x32_bf16 v[80:83], v[156:159], v[188:191], v[80:83]
	v_mfma_f32_16x16x32_bf16 v[68:71], v[140:143], v[210:213], v[68:71]
	v_mfma_f32_16x16x32_bf16 v[64:67], v[156:159], v[210:213], v[64:67]
	v_mfma_f32_16x16x32_bf16 v[124:127], v[144:147], v[168:171], v[124:127]
	v_mfma_f32_16x16x32_bf16 v[120:123], v[160:163], v[168:171], v[120:123]
	v_mfma_f32_16x16x32_bf16 v[100:103], v[144:147], v[176:179], v[100:103]
	v_mfma_f32_16x16x32_bf16 v[96:99], v[160:163], v[176:179], v[96:99]
	v_mfma_f32_16x16x32_bf16 v[84:87], v[144:147], v[206:209], v[84:87]
	v_mfma_f32_16x16x32_bf16 v[80:83], v[160:163], v[206:209], v[80:83]
	v_mfma_f32_16x16x32_bf16 v[68:71], v[144:147], v[214:217], v[68:71]
	v_mfma_f32_16x16x32_bf16 v[64:67], v[160:163], v[214:217], v[64:67]
	s_setprio 0
	s_barrier
	s_add_u32 s46, s48, 0x40000
	s_addc_u32 s47, s49, 0
	s_add_i32 s6, s6, s25
	v_lshl_add_u64 v[218:219], s[46:47], 0, v[138:139]
	s_mov_b32 m0, s6
	ds_read_b128 v[164:167], v222 offset:49152
	ds_read_b128 v[168:171], v222 offset:50176
	ds_read_b128 v[172:175], v222 offset:51200
	ds_read_b128 v[176:179], v222 offset:52224
	ds_read_b128 v[188:191], v222 offset:53248
	ds_read_b128 v[206:209], v222 offset:54272
	ds_read_b128 v[210:213], v222 offset:55296
	ds_read_b128 v[214:217], v222 offset:56320
	global_load_lds_dwordx4 v[218:219], off
	s_add_i32 m0, s6, 0x2000
	v_lshl_add_u64 v[218:219], s[46:47], 0, v[136:137]
	s_add_u32 s46, s48, 0x42000
	s_addc_u32 s47, s49, 0
	s_add_i32 s6, s7, s25
	global_load_lds_dwordx4 v[218:219], off
	v_lshl_add_u64 v[218:219], s[46:47], 0, v[138:139]
	s_mov_b32 m0, s6
	v_lshl_add_u64 v[198:199], v[198:199], 0, s[36:37]
	global_load_lds_dwordx4 v[218:219], off
	v_lshl_add_u64 v[218:219], s[46:47], 0, v[136:137]
	s_add_i32 m0, s6, 0x2000
	s_nop 0
	global_load_lds_dwordx4 v[218:219], off
	s_mov_b32 m0, s58
	s_nop 0
	global_load_lds_dwordx4 v[198:199], off
	v_lshl_add_u64 v[198:199], v[200:201], 0, s[36:37]
	s_mov_b32 m0, s59
	s_nop 0
	global_load_lds_dwordx4 v[198:199], off
	s_add_u32 vcc_lo, vcc_lo, 0x2000
	s_addc_u32 vcc_hi, vcc_hi, 0
	s_mov_b32 m0, 0x22c00
	s_nop 0
	global_load_lds_dwordx4 v224, vcc
	s_waitcnt vmcnt(10)
	s_waitcnt lgkmcnt(0)
	s_barrier
	s_setprio 1
	s_waitcnt lgkmcnt(0)
	v_mfma_f32_16x16x32_bf16 v[60:63], v[112:115], v[164:167], v[60:63]
	v_mfma_f32_16x16x32_bf16 v[56:59], v[128:131], v[164:167], v[56:59]
	v_mfma_f32_16x16x32_bf16 v[44:47], v[112:115], v[172:175], v[44:47]
	v_mfma_f32_16x16x32_bf16 v[40:43], v[128:131], v[172:175], v[40:43]
	v_mfma_f32_16x16x32_bf16 v[28:31], v[112:115], v[188:191], v[28:31]
	v_mfma_f32_16x16x32_bf16 v[24:27], v[128:131], v[188:191], v[24:27]
	v_mfma_f32_16x16x32_bf16 v[12:15], v[112:115], v[210:213], v[12:15]
	v_mfma_f32_16x16x32_bf16 v[8:11], v[128:131], v[210:213], v[8:11]
	v_mfma_f32_16x16x32_bf16 v[60:63], v[116:119], v[168:171], v[60:63]
	v_mfma_f32_16x16x32_bf16 v[56:59], v[132:135], v[168:171], v[56:59]
	v_mfma_f32_16x16x32_bf16 v[44:47], v[116:119], v[176:179], v[44:47]
	v_mfma_f32_16x16x32_bf16 v[40:43], v[132:135], v[176:179], v[40:43]
	v_mfma_f32_16x16x32_bf16 v[28:31], v[116:119], v[206:209], v[28:31]
	v_mfma_f32_16x16x32_bf16 v[24:27], v[132:135], v[206:209], v[24:27]
	v_mfma_f32_16x16x32_bf16 v[12:15], v[116:119], v[214:217], v[12:15]
	v_mfma_f32_16x16x32_bf16 v[8:11], v[132:135], v[214:217], v[8:11]
	s_setprio 0
	s_setprio 1
	v_mfma_f32_16x16x32_bf16 v[52:55], v[140:143], v[164:167], v[52:55]
	v_mfma_f32_16x16x32_bf16 v[48:51], v[156:159], v[164:167], v[48:51]
	v_mfma_f32_16x16x32_bf16 v[36:39], v[140:143], v[172:175], v[36:39]
	v_mfma_f32_16x16x32_bf16 v[32:35], v[156:159], v[172:175], v[32:35]
	v_mfma_f32_16x16x32_bf16 v[20:23], v[140:143], v[188:191], v[20:23]
	v_mfma_f32_16x16x32_bf16 v[16:19], v[156:159], v[188:191], v[16:19]
	v_mfma_f32_16x16x32_bf16 v[4:7], v[140:143], v[210:213], v[4:7]
	v_mfma_f32_16x16x32_bf16 v[0:3], v[156:159], v[210:213], v[0:3]
	v_mfma_f32_16x16x32_bf16 v[52:55], v[144:147], v[168:171], v[52:55]
	v_mfma_f32_16x16x32_bf16 v[48:51], v[160:163], v[168:171], v[48:51]
	v_mfma_f32_16x16x32_bf16 v[36:39], v[144:147], v[176:179], v[36:39]
	v_mfma_f32_16x16x32_bf16 v[32:35], v[160:163], v[176:179], v[32:35]
	v_mfma_f32_16x16x32_bf16 v[20:23], v[144:147], v[206:209], v[20:23]
	v_mfma_f32_16x16x32_bf16 v[16:19], v[160:163], v[206:209], v[16:19]
	v_mfma_f32_16x16x32_bf16 v[4:7], v[144:147], v[214:217], v[4:7]
	v_mfma_f32_16x16x32_bf16 v[0:3], v[160:163], v[214:217], v[0:3]
	s_setprio 0
	s_barrier
	s_add_i32 s77, s77, 2
	s_add_u32 s75, s75, 0x80000
	s_addc_u32 s76, s76, 0
	s_cmp_gt_u32 s77, 29
	s_mov_b64 s[46:47], s[42:43]
	s_cbranch_scc0 .LBB0_727
	v_lshl_or_b32 v188, s12, 8, v221
	v_lshl_add_u32 v190, s13, 8, v197
	v_ashrrev_i32_e32 v189, 31, v188
	v_lshlrev_b64 v[198:199], 2, v[188:189]
	v_ashrrev_i32_e32 v191, 31, v190
	v_lshl_add_u64 v[206:207], s[22:23], 0, v[198:199]
	v_lshlrev_b64 v[200:201], 13, v[190:191]
	v_lshl_add_u64 v[112:113], v[206:207], 0, v[200:201]
	global_load_dwordx4 v[224:227], v[112:113], off offset:16
	global_load_dwordx4 v[228:231], v[112:113], off
	global_load_dwordx4 v[232:235], v[112:113], off offset:528
	global_load_dwordx4 v[244:247], v[112:113], off offset:512
	v_or_b32_e32 v214, 16, v190
	v_ashrrev_i32_e32 v215, 31, v214
	v_or_b32_e32 v210, 32, v190
	v_or_b32_e32 v208, 48, v190
	v_lshlrev_b64 v[218:219], 13, v[214:215]
	v_ashrrev_i32_e32 v211, 31, v210
	v_ashrrev_i32_e32 v209, 31, v208
	v_lshl_add_u64 v[112:113], v[206:207], 0, v[218:219]
	v_lshlrev_b64 v[216:217], 13, v[210:211]
	v_lshlrev_b64 v[212:213], 13, v[208:209]
	global_load_dwordx4 v[172:175], v[112:113], off offset:16
	global_load_dwordx4 v[176:179], v[112:113], off
	global_load_dwordx4 v[164:167], v[112:113], off offset:528
	global_load_dwordx4 v[168:171], v[112:113], off offset:512
	v_lshl_add_u64 v[112:113], v[206:207], 0, v[216:217]
	v_lshl_add_u64 v[116:117], v[206:207], 0, v[212:213]
	global_load_dwordx4 v[156:159], v[112:113], off offset:16
	global_load_dwordx4 v[160:163], v[112:113], off
	global_load_dwordx4 v[128:131], v[112:113], off offset:528
	global_load_dwordx4 v[144:147], v[112:113], off offset:512
	global_load_dwordx4 v[132:135], v[116:117], off offset:16
	global_load_dwordx4 v[140:143], v[116:117], off
	s_nop 0
	global_load_dwordx4 v[112:115], v[116:117], off offset:528
	s_nop 0
	global_load_dwordx4 v[116:119], v[116:117], off offset:512
	v_lshl_add_u64 v[200:201], s[82:83], 0, v[200:201]
	v_lshl_add_u64 v[198:199], v[200:201], 0, v[198:199]
	v_mov_b64_e32 v[200:201], s[4:5]
	s_lshl_b32 s42, s12, 2
	v_mad_i64_i32 v[200:201], s[12:13], v190, s66, v[200:201]
	v_lshl_add_u64 v[200:201], v[188:189], 1, v[200:201]
	s_ashr_i32 s43, s42, 31
	s_waitcnt vmcnt(12)
	v_pk_add_f32 v[148:149], v[148:149], v[224:225]
	v_pk_add_f32 v[154:155], v[154:155], v[230:231]
	v_pk_add_f32 v[152:153], v[152:153], v[228:229]
	v_mul_f32_e32 v224, v155, v155
	v_mul_f32_e32 v223, v153, v153
	v_fmac_f32_e32 v223, v152, v152
	v_fmac_f32_e32 v224, v154, v154
	v_add_f32_e32 v223, v223, v224
	v_mul_f32_e32 v224, v149, v149
	v_pk_add_f32 v[126:127], v[126:127], v[246:247]
	v_pk_add_f32 v[124:125], v[124:125], v[244:245]
	v_pk_add_f32 v[150:151], v[150:151], v[226:227]
	global_store_dwordx4 v[198:199], v[152:155], off
	global_store_dwordx4 v[198:199], v[148:151], off offset:16
	v_fmac_f32_e32 v224, v148, v148
	v_cvt_pk_bf16_f32 v152, v152, v153
	v_cvt_pk_bf16_f32 v153, v154, v155
	v_cvt_pk_bf16_f32 v154, v148, v149
	v_pk_add_f32 v[120:121], v[120:121], v[232:233]
	v_mul_f32_e32 v148, v125, v125
	v_mul_f32_e32 v149, v127, v127
	v_fmac_f32_e32 v148, v124, v124
	v_fmac_f32_e32 v149, v126, v126
	v_add_f32_e32 v148, v148, v149
	v_mul_f32_e32 v149, v121, v121
	v_cvt_pk_bf16_f32 v155, v150, v151
	global_store_dwordx4 v[200:201], v[152:155], off
	v_pk_add_f32 v[122:123], v[122:123], v[234:235]
	global_store_dwordx4 v[198:199], v[124:127], off offset:512
	global_store_dwordx4 v[198:199], v[120:123], off offset:528
	v_fmac_f32_e32 v149, v120, v120
	v_cvt_pk_bf16_f32 v124, v124, v125
	v_cvt_pk_bf16_f32 v125, v126, v127
	v_cvt_pk_bf16_f32 v126, v120, v121
	v_add_f32_e32 v223, v223, v224
	v_and_b32_e32 v121, 64, v239
	v_mul_f32_e32 v224, v151, v151
	v_add_f32_e32 v148, v148, v149
	v_mul_f32_e32 v149, v123, v123
	v_xor_b32_e32 v120, 16, v239
	v_add_u32_e32 v121, 64, v121
	v_fmac_f32_e32 v224, v150, v150
	v_fmac_f32_e32 v149, v122, v122
	v_cmp_lt_i32_e32 vcc, v120, v121
	v_add_f32_e32 v223, v224, v223
	v_add_f32_e32 v148, v149, v148
	v_cndmask_b32_e32 v120, v239, v120, vcc
	v_add_f32_e32 v148, v223, v148
	v_cvt_pk_bf16_f32 v127, v122, v123
	global_store_dwordx4 v[200:201], v[124:127], off offset:256
	v_xor_b32_e32 v122, 32, v239
	v_cmp_lt_i32_e32 vcc, v122, v121
	v_lshlrev_b32_e32 v126, 2, v120
	v_mov_b32_e32 v120, v148
	s_nop 1
	v_permlane16_swap_b32_e32 v120, v148
	v_cndmask_b32_e32 v121, v239, v122, vcc
	v_lshlrev_b32_e32 v127, 2, v121
	s_waitcnt lgkmcnt(0)
	v_add_f32_e32 v120, v148, v120
	v_mov_b32_e32 v121, v120
	s_nop 1
	v_permlane32_swap_b32_e32 v121, v120
	s_and_saveexec_b64 s[46:47], s[38:39]
	s_cbranch_execz .LBB0_730
	v_lshlrev_b64 v[122:123], 7, v[190:191]
	v_lshl_add_u64 v[122:123], s[94:95], 0, v[122:123]
	v_lshl_add_u64 v[122:123], s[42:43], 2, v[122:123]
	s_lshl_b32 s30, s57, 2
	v_lshl_add_u64 v[122:123], v[122:123], 0, s[30:31]
	s_waitcnt lgkmcnt(0)
	v_add_f32_e32 v120, v120, v121
	global_store_dword v[122:123], v120, off
